# P1 start of odd-loc workgroups delayed ~1.8 us (de-phases the lockstep epilogue store bursts within an XCC)
# speedup vs baseline: 1.0008x; 1.0008x over previous
; __global__ void __launch_bounds__(512, 2) mk_fwd(Args args) {
;     ...
;             if (STAGGER_TICKS > 0) { const unsigned long long t0_ = __builtin_amdgcn_s_memrealtime(), w_ = (unsigned long long)((cid >> 3) & 3) * STAGGER_TICKS; while (__builtin_amdgcn_s_memrealtime() - t0_ < w_) __builtin_amdgcn_s_sleep(16); }
;             gemm_phase<P1Prog, true, false, false, P1_SLACK>(F.lds, 1024, P, F.wave, tg_k[0], tg_e[0]);
.LBB0_190:
	v_readlane_b32 s98, v254, 49
	s_nop 3
	s_lshr_b32 s98, s98, 3
	s_and_b32 s98, s98, 1
	s_cmp_eq_u32 s98, 0
	s_cbranch_scc1 .Lskew_done
.Lskew_loop:
	s_sleep 60
	s_sub_u32 s98, s98, 1
	s_cmp_lg_u32 s98, 0
	s_cbranch_scc1 .Lskew_loop
